# v029 + LayerNorm row loop: all gamma/beta loads issued at the top of each row (no load wait behind nt stores), butterfly xor1/2/4/8 via DPP
# speedup vs baseline: 1.0158x; 1.0158x over previous
; DI float bflo(unsigned u) { return __uint_as_float(u << 16); }
; DI float bfhi(unsigned u) { return __uint_as_float(u & 0xffff0000u); }
; DI void ln_row(Ctx A_, int m, int lane) {
;     const v4u* pr = (const v4u*)(PRE_ + (size_t)m * D) + lane;
;     float v[4][8]; float s = 0.f;
; #pragma unroll
;     for (int j = 0; j < 4; ++j) { const v4u w = pr[64 * j];
;         v[j][0] = bflo(w.x); v[j][1] = bfhi(w.x); v[j][2] = bflo(w.y); v[j][3] = bfhi(w.y); v[j][4] = bflo(w.z); v[j][5] = bfhi(w.z); v[j][6] = bflo(w.w); v[j][7] = bfhi(w.w);
; #pragma unroll
;         for (int e = 0; e < 8; ++e) s += v[j][e]; }
;     const float mean = wave_sum(s) * (1.0f / D); float s2 = 0.f;
; #pragma unroll
;     for (int j = 0; j < 4; ++j)
; #pragma unroll
;         for (int e = 0; e < 8; ++e) { v[j][e] -= mean; s2 += v[j][e] * v[j][e]; }
;     const float rstd = 1.0f / sqrtf(wave_sum(s2) * (1.0f / D) + NORM_EPS);
.LBB0_1137:
	global_load_dwordx4 v[56:59], v[34:35], off
	global_load_dwordx4 v[60:63], v[34:35], off offset:3072
	global_load_dwordx4 v[64:67], v[34:35], off offset:1024
	global_load_dwordx4 v[68:71], v[34:35], off offset:2048
	global_load_dwordx4 v[2:5], v[22:23], off offset:16
	global_load_dwordx4 v[10:13], v[22:23], off
	global_load_dwordx4 v[6:9], v[24:25], off offset:16
	global_load_dwordx4 v[14:17], v[24:25], off
	global_load_dwordx4 v[120:123], v[24:25], off offset:2048
	global_load_dwordx4 v[124:127], v[22:23], off offset:2048
	global_load_dwordx4 v[128:131], v[22:23], off offset:2064
	global_load_dwordx4 v[132:135], v[24:25], off offset:2064
	global_load_dwordx4 v[136:139], v[28:29], off
	global_load_dwordx4 v[140:143], v[26:27], off
	global_load_dwordx4 v[144:147], v[26:27], off offset:16
	global_load_dwordx4 v[148:151], v[28:29], off offset:16
	global_load_dwordx4 v[152:155], v[32:33], off
	global_load_dwordx4 v[156:159], v[30:31], off
	global_load_dwordx4 v[160:163], v[30:31], off offset:16
	global_load_dwordx4 v[164:167], v[32:33], off offset:16
	v_lshl_add_u64 v[38:39], v[36:37], 0, s[10:11]
	s_add_u32 s10, s10, 0x2000
	s_addc_u32 s11, s11, 0
	v_lshl_add_u64 v[34:35], v[34:35], 0, s[8:9]
	s_cmpk_lg_u32 s10, 0x8000
	s_waitcnt vmcnt(19)
	v_lshlrev_b32_e32 v72, 16, v56
	v_and_b32_e32 v73, 0xffff0000, v56
	v_add_f32_e32 v18, 0, v72
	v_lshlrev_b32_e32 v56, 16, v57
	v_add_f32_e32 v18, v18, v73
	v_and_b32_e32 v57, 0xffff0000, v57
	v_add_f32_e32 v18, v18, v56
	v_lshlrev_b32_e32 v76, 16, v58
	v_add_f32_e32 v18, v18, v57
	v_and_b32_e32 v77, 0xffff0000, v58
	v_add_f32_e32 v18, v18, v76
	v_lshlrev_b32_e32 v58, 16, v59
	v_add_f32_e32 v18, v18, v77
	v_and_b32_e32 v59, 0xffff0000, v59
	v_add_f32_e32 v18, v18, v58
	s_waitcnt vmcnt(17)
	v_lshlrev_b32_e32 v78, 16, v64
	v_add_f32_e32 v18, v18, v59
	v_and_b32_e32 v79, 0xffff0000, v64
	v_add_f32_e32 v18, v18, v78
	v_lshlrev_b32_e32 v64, 16, v65
	v_add_f32_e32 v18, v18, v79
	v_and_b32_e32 v65, 0xffff0000, v65
	v_add_f32_e32 v18, v18, v64
	v_lshlrev_b32_e32 v80, 16, v66
	v_add_f32_e32 v18, v18, v65
	v_and_b32_e32 v81, 0xffff0000, v66
	v_add_f32_e32 v18, v18, v80
	v_lshlrev_b32_e32 v66, 16, v67
	v_add_f32_e32 v18, v18, v81
	v_and_b32_e32 v67, 0xffff0000, v67
	v_add_f32_e32 v18, v18, v66
	s_waitcnt vmcnt(16)
	v_lshlrev_b32_e32 v82, 16, v68
	v_add_f32_e32 v18, v18, v67
	v_and_b32_e32 v83, 0xffff0000, v68
	v_add_f32_e32 v18, v18, v82
	v_lshlrev_b32_e32 v68, 16, v69
	v_add_f32_e32 v18, v18, v83
	v_and_b32_e32 v69, 0xffff0000, v69
	v_add_f32_e32 v18, v18, v68
	v_lshlrev_b32_e32 v84, 16, v70
	v_add_f32_e32 v18, v18, v69
	v_and_b32_e32 v85, 0xffff0000, v70
	v_add_f32_e32 v18, v18, v84
	v_lshlrev_b32_e32 v70, 16, v71
	v_add_f32_e32 v18, v18, v85
	v_and_b32_e32 v71, 0xffff0000, v71
	v_add_f32_e32 v18, v18, v70
	v_lshlrev_b32_e32 v86, 16, v60
	v_add_f32_e32 v18, v18, v71
	v_and_b32_e32 v87, 0xffff0000, v60
	v_add_f32_e32 v18, v18, v86
	v_lshlrev_b32_e32 v60, 16, v61
	v_add_f32_e32 v18, v18, v87
	v_and_b32_e32 v61, 0xffff0000, v61
	v_add_f32_e32 v18, v18, v60
	v_lshlrev_b32_e32 v88, 16, v62
	v_add_f32_e32 v18, v18, v61
	v_and_b32_e32 v89, 0xffff0000, v62
	v_add_f32_e32 v18, v18, v88
	v_lshlrev_b32_e32 v75, 16, v63
	v_add_f32_e32 v18, v18, v89
	v_and_b32_e32 v74, 0xffff0000, v63
	v_add_f32_e32 v18, v18, v75
	v_add_f32_e32 v18, v18, v74
	s_nop 1
	v_mov_b32_dpp v62, v18 quad_perm:[1,0,3,2] row_mask:0xf bank_mask:0xf
	s_waitcnt lgkmcnt(0)
	v_add_f32_e32 v18, v18, v62
	s_nop 1
	v_mov_b32_dpp v62, v18 quad_perm:[2,3,0,1] row_mask:0xf bank_mask:0xf
	s_waitcnt lgkmcnt(0)
	v_add_f32_e32 v18, v18, v62
	s_nop 1
	v_mov_b32_dpp v62, v18 row_half_mirror row_mask:0xf bank_mask:0xf
	s_waitcnt lgkmcnt(0)
	v_add_f32_e32 v18, v18, v62
	s_nop 1
	v_mov_b32_dpp v62, v18 row_mirror row_mask:0xf bank_mask:0xf
	s_waitcnt lgkmcnt(0)
	v_add_f32_e32 v18, v18, v62
	ds_bpermute_b32 v62, v54, v18
	s_waitcnt lgkmcnt(0)
	v_add_f32_e32 v18, v18, v62
	ds_bpermute_b32 v62, v55, v18
	s_waitcnt lgkmcnt(0)
	v_add_f32_e32 v18, v18, v62
	v_mul_f32_e32 v18, 0x3a000000, v18
	v_pk_add_f32 v[62:63], v[72:73], v[18:19] op_sel_hi:[1,0] neg_lo:[0,1] neg_hi:[0,1]
	v_pk_add_f32 v[56:57], v[56:57], v[18:19] op_sel_hi:[1,0] neg_lo:[0,1] neg_hi:[0,1]
	v_pk_add_f32 v[72:73], v[76:77], v[18:19] op_sel_hi:[1,0] neg_lo:[0,1] neg_hi:[0,1]
	v_pk_add_f32 v[76:77], v[78:79], v[18:19] op_sel_hi:[1,0] neg_lo:[0,1] neg_hi:[0,1]
	v_pk_add_f32 v[78:79], v[80:81], v[18:19] op_sel_hi:[1,0] neg_lo:[0,1] neg_hi:[0,1]
	v_pk_add_f32 v[80:81], v[82:83], v[18:19] op_sel_hi:[1,0] neg_lo:[0,1] neg_hi:[0,1]
	v_pk_add_f32 v[82:83], v[84:85], v[18:19] op_sel_hi:[1,0] neg_lo:[0,1] neg_hi:[0,1]
	v_pk_add_f32 v[84:85], v[86:87], v[18:19] op_sel_hi:[1,0] neg_lo:[0,1] neg_hi:[0,1]
	v_pk_add_f32 v[86:87], v[88:89], v[18:19] op_sel_hi:[1,0] neg_lo:[0,1] neg_hi:[0,1]
	v_pk_mul_f32 v[88:89], v[62:63], v[62:63]
	v_pk_add_f32 v[58:59], v[58:59], v[18:19] op_sel_hi:[1,0] neg_lo:[0,1] neg_hi:[0,1]
	v_pk_add_f32 v[64:65], v[64:65], v[18:19] op_sel_hi:[1,0] neg_lo:[0,1] neg_hi:[0,1]
	v_pk_add_f32 v[66:67], v[66:67], v[18:19] op_sel_hi:[1,0] neg_lo:[0,1] neg_hi:[0,1]
	v_pk_add_f32 v[68:69], v[68:69], v[18:19] op_sel_hi:[1,0] neg_lo:[0,1] neg_hi:[0,1]
	v_pk_add_f32 v[70:71], v[70:71], v[18:19] op_sel_hi:[1,0] neg_lo:[0,1] neg_hi:[0,1]
	v_pk_add_f32 v[60:61], v[60:61], v[18:19] op_sel_hi:[1,0] neg_lo:[0,1] neg_hi:[0,1]
	v_pk_add_f32 v[74:75], v[74:75], v[18:19] op_sel_hi:[1,0] neg_lo:[0,1] neg_hi:[0,1]
	v_pk_mul_f32 v[90:91], v[56:57], v[56:57]
	v_add_f32_e32 v18, v88, v89
	v_add_f32_e32 v18, v90, v18
	v_pk_mul_f32 v[92:93], v[72:73], v[72:73]
	v_add_f32_e32 v18, v91, v18
	v_add_f32_e32 v18, v92, v18
; DI void ln_row(Ctx A_, int m, int lane) {
;     ...
;     const float mean = wave_sum(s) * (1.0f / D); float s2 = 0.f;
; #pragma unroll
;     for (int j = 0; j < 4; ++j)
; #pragma unroll
;         for (int e = 0; e < 8; ++e) { v[j][e] -= mean; s2 += v[j][e] * v[j][e]; }
;     const float rstd = 1.0f / sqrtf(wave_sum(s2) * (1.0f / D) + NORM_EPS);
; #pragma unroll
;     for (int j = 0; j < 4; ++j) { const int c0 = 512 * j + 8 * lane;
;         const v4f g0 = *(const v4f*)(LN_G + c0), g1 = *(const v4f*)(LN_G + c0 + 4), b0 = *(const v4f*)(LN_B + c0), b1 = *(const v4f*)(LN_B + c0 + 4);
;         float* o = OUT_ + (size_t)m * D + c0;
;         __builtin_nontemporal_store((v4f){v[j][0] * rstd * g0.x + b0.x, v[j][1] * rstd * g0.y + b0.y, v[j][2] * rstd * g0.z + b0.z, v[j][3] * rstd * g0.w + b0.w}, (v4f*)o);
;         __builtin_nontemporal_store((v4f){v[j][4] * rstd * g1.x + b1.x, v[j][5] * rstd * g1.y + b1.y, v[j][6] * rstd * g1.z + b1.z, v[j][7] * rstd * g1.w + b1.w}, (v4f*)(o + 4)); }
	v_pk_mul_f32 v[94:95], v[58:59], v[58:59]
	v_add_f32_e32 v18, v93, v18
	v_add_f32_e32 v18, v94, v18
	v_pk_mul_f32 v[96:97], v[76:77], v[76:77]
	v_add_f32_e32 v18, v95, v18
	v_add_f32_e32 v18, v96, v18
	v_pk_mul_f32 v[98:99], v[64:65], v[64:65]
	v_add_f32_e32 v18, v97, v18
	v_add_f32_e32 v18, v98, v18
	v_pk_mul_f32 v[100:101], v[78:79], v[78:79]
	v_add_f32_e32 v18, v99, v18
	v_add_f32_e32 v18, v100, v18
	v_pk_mul_f32 v[102:103], v[66:67], v[66:67]
	v_add_f32_e32 v18, v101, v18
	v_add_f32_e32 v18, v102, v18
	v_pk_mul_f32 v[104:105], v[80:81], v[80:81]
	v_add_f32_e32 v18, v103, v18
	v_add_f32_e32 v18, v104, v18
	v_pk_mul_f32 v[106:107], v[68:69], v[68:69]
	v_add_f32_e32 v18, v105, v18
	v_add_f32_e32 v18, v106, v18
	v_pk_mul_f32 v[108:109], v[82:83], v[82:83]
	v_add_f32_e32 v18, v107, v18
	v_add_f32_e32 v18, v108, v18
	v_pk_mul_f32 v[110:111], v[70:71], v[70:71]
	v_add_f32_e32 v18, v109, v18
	v_add_f32_e32 v18, v110, v18
	v_pk_mul_f32 v[112:113], v[84:85], v[84:85]
	v_add_f32_e32 v18, v111, v18
	v_add_f32_e32 v18, v112, v18
	v_pk_mul_f32 v[114:115], v[60:61], v[60:61]
	v_add_f32_e32 v18, v113, v18
	v_add_f32_e32 v18, v114, v18
	v_pk_mul_f32 v[116:117], v[86:87], v[86:87]
	v_add_f32_e32 v18, v115, v18
	v_add_f32_e32 v18, v116, v18
	v_pk_mul_f32 v[118:119], v[74:75], v[74:75]
	v_add_f32_e32 v18, v117, v18
	v_add_f32_e32 v18, v119, v18
	v_add_f32_e32 v18, v118, v18
	s_nop 1
	v_mov_b32_dpp v88, v18 quad_perm:[1,0,3,2] row_mask:0xf bank_mask:0xf
	s_waitcnt lgkmcnt(0)
	v_add_f32_e32 v18, v18, v88
	s_nop 1
	v_mov_b32_dpp v88, v18 quad_perm:[2,3,0,1] row_mask:0xf bank_mask:0xf
	s_waitcnt lgkmcnt(0)
	v_add_f32_e32 v18, v18, v88
	s_nop 1
	v_mov_b32_dpp v88, v18 row_half_mirror row_mask:0xf bank_mask:0xf
	s_waitcnt lgkmcnt(0)
	v_add_f32_e32 v18, v18, v88
	s_nop 1
	v_mov_b32_dpp v88, v18 row_mirror row_mask:0xf bank_mask:0xf
	s_waitcnt lgkmcnt(0)
	v_add_f32_e32 v18, v18, v88
	ds_bpermute_b32 v88, v54, v18
	s_waitcnt lgkmcnt(0)
	v_add_f32_e32 v18, v18, v88
	ds_bpermute_b32 v88, v55, v18
	s_waitcnt lgkmcnt(0)
	v_add_f32_e32 v18, v18, v88
	v_fmamk_f32 v18, v18, 0x3a000000, v41
	v_mul_f32_e32 v88, 0x4f800000, v18
	v_cmp_gt_f32_e32 vcc, s24, v18
	s_nop 1
	v_cndmask_b32_e32 v18, v18, v88, vcc
	v_sqrt_f32_e32 v88, v18
	s_nop 0
	v_add_u32_e32 v89, -1, v88
	v_add_u32_e32 v90, 1, v88
	v_fma_f32 v91, -v89, v88, v18
	v_fma_f32 v92, -v90, v88, v18
	v_cmp_ge_f32_e64 s[2:3], 0, v91
	s_nop 1
	v_cndmask_b32_e64 v88, v88, v89, s[2:3]
	v_cmp_lt_f32_e64 s[2:3], 0, v92
	s_nop 1
	v_cndmask_b32_e64 v88, v88, v90, s[2:3]
	v_mul_f32_e32 v89, 0x37800000, v88
	v_cndmask_b32_e32 v88, v88, v89, vcc
	v_cmp_class_f32_e32 vcc, v18, v42
	s_nop 1
	v_cndmask_b32_e32 v18, v88, v18, vcc
	v_div_scale_f32 v88, s[2:3], v18, v18, 1.0
	v_rcp_f32_e32 v90, v88
	v_div_scale_f32 v89, vcc, 1.0, v18, 1.0
	v_fma_f32 v91, -v88, v90, 1.0
	v_fmac_f32_e32 v90, v91, v90
	v_mul_f32_e32 v91, v89, v90
	v_fma_f32 v92, -v88, v91, v89
	v_fmac_f32_e32 v91, v92, v90
	v_fma_f32 v88, -v88, v91, v89
	v_div_fmas_f32 v88, v88, v90, v91
	v_div_fixup_f32 v18, v88, v18, 1.0
	v_pk_mul_f32 v[62:63], v[62:63], v[18:19] op_sel_hi:[1,0]
	v_pk_mul_f32 v[56:57], v[56:57], v[18:19] op_sel_hi:[1,0]
	v_pk_mul_f32 v[72:73], v[72:73], v[18:19] op_sel_hi:[1,0]
	v_pk_mul_f32 v[58:59], v[58:59], v[18:19] op_sel_hi:[1,0]
	s_waitcnt vmcnt(12)
	v_pk_fma_f32 v[12:13], v[12:13], v[56:57], v[16:17]
	v_pk_fma_f32 v[10:11], v[10:11], v[62:63], v[14:15]
	v_pk_fma_f32 v[4:5], v[4:5], v[58:59], v[8:9]
	v_pk_fma_f32 v[2:3], v[2:3], v[72:73], v[6:7]
	global_store_dwordx4 v[38:39], v[10:13], off nt
	global_store_dwordx4 v[38:39], v[2:5], off offset:16 nt
	s_nop 0
	v_pk_mul_f32 v[56:57], v[64:65], v[18:19] op_sel_hi:[1,0]
	v_pk_mul_f32 v[58:59], v[76:77], v[18:19] op_sel_hi:[1,0]
	v_pk_mul_f32 v[62:63], v[66:67], v[18:19] op_sel_hi:[1,0]
	v_pk_mul_f32 v[64:65], v[78:79], v[18:19] op_sel_hi:[1,0]
	s_waitcnt vmcnt(12)
	v_pk_fma_f32 v[120:121], v[124:125], v[58:59], v[120:121]
	v_pk_fma_f32 v[122:123], v[126:127], v[56:57], v[122:123]
	s_waitcnt vmcnt(10)
	v_pk_fma_f32 v[124:125], v[128:129], v[64:65], v[132:133]
	v_pk_fma_f32 v[126:127], v[130:131], v[62:63], v[134:135]
	global_store_dwordx4 v[38:39], v[120:123], off offset:2048 nt
	global_store_dwordx4 v[38:39], v[124:127], off offset:2064 nt
	s_nop 0
	v_add_co_u32_e32 v38, vcc, s23, v38
	v_pk_mul_f32 v[56:57], v[68:69], v[18:19] op_sel_hi:[1,0]
	v_pk_mul_f32 v[58:59], v[80:81], v[18:19] op_sel_hi:[1,0]
	v_addc_co_u32_e32 v39, vcc, 0, v39, vcc
	v_pk_mul_f32 v[62:63], v[70:71], v[18:19] op_sel_hi:[1,0]
	v_pk_mul_f32 v[64:65], v[82:83], v[18:19] op_sel_hi:[1,0]
	s_waitcnt vmcnt(10)
	v_pk_fma_f32 v[136:137], v[140:141], v[58:59], v[136:137]
	v_pk_fma_f32 v[138:139], v[142:143], v[56:57], v[138:139]
	s_waitcnt vmcnt(8)
	v_pk_fma_f32 v[140:141], v[144:145], v[64:65], v[148:149]
	v_pk_fma_f32 v[142:143], v[146:147], v[62:63], v[150:151]
	global_store_dwordx4 v[38:39], v[136:139], off nt
	global_store_dwordx4 v[38:39], v[140:143], off offset:16 nt
	s_nop 0
	v_pk_mul_f32 v[56:57], v[60:61], v[18:19] op_sel_hi:[1,0]
	v_pk_mul_f32 v[58:59], v[84:85], v[18:19] op_sel_hi:[1,0]
	v_pk_mul_f32 v[60:61], v[86:87], v[18:19] op_sel_hi:[1,0]
	v_pk_mul_f32 v[62:63], v[74:75], v[18:19] op_sel_hi:[1,0]
	s_waitcnt vmcnt(8)
	v_pk_fma_f32 v[152:153], v[156:157], v[58:59], v[152:153]
	v_pk_fma_f32 v[154:155], v[158:159], v[56:57], v[154:155]
	s_waitcnt vmcnt(6)
	v_pk_fma_f32 v[156:157], v[160:161], v[60:61], v[164:165]
	v_pk_fma_f32 v[158:159], v[162:163], v[62:63], v[166:167] op_sel:[0,1,0] op_sel_hi:[1,0,1]
	global_store_dwordx4 v[38:39], v[152:155], off offset:2048 nt
	global_store_dwordx4 v[38:39], v[156:159], off offset:2064 nt
	s_cbranch_scc1 .LBB0_1137
	s_add_i32 s20, s20, 1
	s_mov_b64 s[2:3], 0
	s_branch .LBB0_1106
